# E49: E48 with the idle-WG weight conversion prefetching two jobs ahead (3 register sets, 3 LDS tile buffers)
# baseline (speedup 1.0000x reference)
; __device__ __forceinline__ int tid_() { int t = threadIdx.x; asm volatile("" : "+v"(t)); return t; }
; __device__ __forceinline__ void conv_matrix(const float* __restrict__ src, int K, int N, int Npad, bf16_t* __restrict__ dst, const float* __restrict__ scale, float* tile) {
;   const int nk = K / 64, nn = Npad / 64, tot = nk * nn;
;   const int tid = tid_(), tx = tid & 63, ty = tid >> 6, nl = tid >> 3, ks = (tid & 7) * 8;
;   for (int i0 = blockIdx.x; i0 < tot; i0 += 2 * gridDim.x) {
;     const int i1 = i0 + gridDim.x; const bool has1 = i1 < tot;
;     const int k0a = (i0 % nk) * 64, n0a = (i0 / nk) * 64, k0b = has1 ? (i1 % nk) * 64 : 0, n0b = has1 ? (i1 / nk) * 64 : 0;
;     float va[8], vb[8];
; #pragma unroll
;     for (int i = 0; i < 8; ++i) { const int k = k0a + ty + 8 * i, n = n0a + tx; float v = (n < N) ? src[(size_t)k * N + n] : 0.f; if (scale) v *= scale[k]; va[i] = v; }
;     if (has1) {
; #pragma unroll
;       for (int i = 0; i < 8; ++i) { const int k = k0b + ty + 8 * i, n = n0b + tx; float v = (n < N) ? src[(size_t)k * N + n] : 0.f; if (scale) v *= scale[k]; vb[i] = v; }
;     }
.LBB0_1028:
	s_cmp_lt_u32 s2, 12
	s_cbranch_scc1 .Lcvo_skip
	v_writelane_b32 v255, s4, 46
	v_writelane_b32 v255, s5, 47
	v_writelane_b32 v255, s10, 48
	v_writelane_b32 v255, s11, 49
	v_writelane_b32 v255, s12, 50
	v_writelane_b32 v255, s13, 51
	v_writelane_b32 v255, s14, 52
	v_writelane_b32 v255, s15, 53
	v_writelane_b32 v255, s20, 54
	v_writelane_b32 v255, s21, 55
	v_writelane_b32 v255, s22, 56
	v_writelane_b32 v255, s23, 57
	v_writelane_b32 v255, s24, 58
	v_writelane_b32 v255, s25, 59
	v_writelane_b32 v255, s26, 60
	v_writelane_b32 v255, s27, 61
	s_load_dwordx2 s[10:11], s[0:1], 0x40
	s_load_dwordx2 s[12:13], s[0:1], 0x48
	s_load_dwordx2 s[14:15], s[0:1], 0xd8
	v_and_b32_e32 v1, 63, v187
	v_lshrrev_b32_e32 v7, 6, v187
	v_lshrrev_b32_e32 v4, 3, v187
	v_and_b32_e32 v5, 7, v187
	s_nop 1
	v_readfirstlane_b32 s6, v7
	v_readlane_b32 s7, v255, 32
	v_mul_u32_u24_e32 v2, 0x41, v7
	v_add_u32_e32 v2, v2, v1
	v_lshlrev_b32_e32 v2, 2, v2
	v_add_u32_e32 v2, 16, v2
	v_lshlrev_b32_e32 v1, 2, v1
	v_mul_u32_u24_e32 v3, 0x208, v5
	v_add_u32_e32 v3, v3, v4
	v_lshlrev_b32_e32 v3, 2, v3
	v_add_u32_e32 v3, 16, v3
	v_lshlrev_b32_e32 v5, 4, v5
	s_lshl_b32 s7, s7, 24
	s_waitcnt lgkmcnt(0)
	s_add_u32 s10, s10, s7
	s_addc_u32 s11, s11, 0
	s_add_u32 s12, s12, s7
	s_addc_u32 s13, s13, 0
	s_sub_u32 s4, s2, 12
	s_cmp_lt_u32 s4, 0x400
	s_cselect_b32 s20, 4, 6
	s_cselect_b32 s21, 14, 12
	s_cselect_b32 s26, s10, s12
	s_cselect_b32 s27, s11, s13
	s_and_b32 s22, s4, 0x3ff
	s_lshl_b32 s25, 1, s20
	s_sub_u32 s25, s25, 1
	s_and_b32 s23, s22, s25
	s_lshr_b32 s24, s22, s20
	s_lshl_b32 s23, s23, 6
	s_add_u32 s23, s23, s6
	s_lshl_b32 s23, s23, s21
	s_lshl_b32 s24, s24, 8
	s_add_u32 s23, s23, s24
	s_add_u32 s26, s26, s23
	s_addc_u32 s27, s27, 0
	s_add_u32 s25, s21, 3
	s_lshl_b32 s25, 1, s25
	v_add_u32_e32 v21, s25, v1
	v_add_u32_e32 v22, s25, v21
	v_add_u32_e32 v23, s25, v22
	v_add_u32_e32 v24, s25, v23
	v_add_u32_e32 v25, s25, v24
	v_add_u32_e32 v26, s25, v25
	v_add_u32_e32 v27, s25, v26
	global_load_dword v30, v1, s[26:27]
	global_load_dword v31, v21, s[26:27]
	global_load_dword v32, v22, s[26:27]
	global_load_dword v33, v23, s[26:27]
	global_load_dword v34, v24, s[26:27]
	global_load_dword v35, v25, s[26:27]
	global_load_dword v36, v26, s[26:27]
	global_load_dword v37, v27, s[26:27]
	s_add_u32 s5, s4, 244
	s_cmp_lt_u32 s5, 0x400
	s_cselect_b32 s20, 4, 6
	s_cselect_b32 s21, 14, 12
	s_cselect_b32 s26, s10, s12
	s_cselect_b32 s27, s11, s13
	s_and_b32 s22, s5, 0x3ff
	s_lshl_b32 s25, 1, s20
	s_sub_u32 s25, s25, 1
	s_and_b32 s23, s22, s25
	s_lshr_b32 s24, s22, s20
	s_lshl_b32 s23, s23, 6
	s_add_u32 s23, s23, s6
	s_lshl_b32 s23, s23, s21
	s_lshl_b32 s24, s24, 8
	s_add_u32 s23, s23, s24
	s_add_u32 s26, s26, s23
	s_addc_u32 s27, s27, 0
	s_add_u32 s25, s21, 3
	s_lshl_b32 s25, 1, s25
	v_add_u32_e32 v21, s25, v1
	v_add_u32_e32 v22, s25, v21
	v_add_u32_e32 v23, s25, v22
	v_add_u32_e32 v24, s25, v23
	v_add_u32_e32 v25, s25, v24
	v_add_u32_e32 v26, s25, v25
	v_add_u32_e32 v27, s25, v26
	global_load_dword v40, v1, s[26:27]
	global_load_dword v41, v21, s[26:27]
	global_load_dword v42, v22, s[26:27]
	global_load_dword v43, v23, s[26:27]
	global_load_dword v44, v24, s[26:27]
	global_load_dword v45, v25, s[26:27]
	global_load_dword v46, v26, s[26:27]
	global_load_dword v47, v27, s[26:27]
	s_mov_b32 s7, 0
.Lcvo_j0:
	s_add_u32 s5, s4, 488
	s_cmp_lt_u32 s5, 0x800
	s_cbranch_scc0 .Lcvo_t0
	s_cmp_lt_u32 s5, 0x400
	s_cselect_b32 s20, 4, 6
	s_cselect_b32 s21, 14, 12
	s_cselect_b32 s26, s10, s12
	s_cselect_b32 s27, s11, s13
	s_and_b32 s22, s5, 0x3ff
	s_lshl_b32 s25, 1, s20
	s_sub_u32 s25, s25, 1
	s_and_b32 s23, s22, s25
	s_lshr_b32 s24, s22, s20
	s_lshl_b32 s23, s23, 6
	s_add_u32 s23, s23, s6
	s_lshl_b32 s23, s23, s21
	s_lshl_b32 s24, s24, 8
	s_add_u32 s23, s23, s24
	s_add_u32 s26, s26, s23
	s_addc_u32 s27, s27, 0
	s_add_u32 s25, s21, 3
	s_lshl_b32 s25, 1, s25
	v_add_u32_e32 v21, s25, v1
	v_add_u32_e32 v22, s25, v21
	v_add_u32_e32 v23, s25, v22
	v_add_u32_e32 v24, s25, v23
	v_add_u32_e32 v25, s25, v24
	v_add_u32_e32 v26, s25, v25
	v_add_u32_e32 v27, s25, v26
	global_load_dword v8, v1, s[26:27]
	global_load_dword v9, v21, s[26:27]
	global_load_dword v10, v22, s[26:27]
	global_load_dword v11, v23, s[26:27]
	global_load_dword v12, v24, s[26:27]
	global_load_dword v13, v25, s[26:27]
	global_load_dword v14, v26, s[26:27]
	global_load_dword v15, v27, s[26:27]
	s_cmp_lt_u32 s7, 2
	s_cbranch_scc1 .Lcvo_w0
	s_waitcnt vmcnt(18)
	s_branch .Lcvo_p0
.Lcvo_w0:
	s_waitcnt vmcnt(16)
	s_branch .Lcvo_p0
.Lcvo_t0:
	s_add_u32 s5, s4, 244
	s_cmp_lt_u32 s5, 0x800
	s_cbranch_scc0 .Lcvo_z0
	s_waitcnt vmcnt(8)
	s_branch .Lcvo_p0

; __device__ __forceinline__ unsigned cvt_pk_bf16(float lo, float hi) { unsigned r; asm volatile("v_cvt_pk_bf16_f32 %0, %1, %2" : "=v"(r) : "v"(lo), "v"(hi)); return r; }
; __device__ __forceinline__ void conv_matrix(const float* __restrict__ src, int K, int N, int Npad, bf16_t* __restrict__ dst, const float* __restrict__ scale, float* tile) {
;     ...
;   for (int i0 = blockIdx.x; i0 < tot; i0 += 2 * gridDim.x) {
;     const int i1 = i0 + gridDim.x; const bool has1 = i1 < tot;
;     const int k0a = (i0 % nk) * 64, n0a = (i0 / nk) * 64, k0b = has1 ? (i1 % nk) * 64 : 0, n0b = has1 ? (i1 / nk) * 64 : 0;
;     float va[8], vb[8];
; #pragma unroll
;     for (int i = 0; i < 8; ++i) { const int k = k0a + ty + 8 * i, n = n0a + tx; float v = (n < N) ? src[(size_t)k * N + n] : 0.f; if (scale) v *= scale[k]; va[i] = v; }
;     if (has1) {
; #pragma unroll
;       for (int i = 0; i < 8; ++i) { const int k = k0b + ty + 8 * i, n = n0b + tx; float v = (n < N) ? src[(size_t)k * N + n] : 0.f; if (scale) v *= scale[k]; vb[i] = v; }
;     }
;     __syncthreads();
; #pragma unroll
;     for (int i = 0; i < 8; ++i) { tile[(ty + 8 * i) * 65 + tx] = va[i]; if (has1) tile[4160 + (ty + 8 * i) * 65 + tx] = vb[i]; }
;     __syncthreads();
;     { float v[8];
; #pragma unroll
;       for (int j = 0; j < 8; ++j) v[j] = tile[(ks + j) * 65 + nl];
;       u32x4 w = {cvt_pk_bf16(v[0], v[1]), cvt_pk_bf16(v[2], v[3]), cvt_pk_bf16(v[4], v[5]), cvt_pk_bf16(v[6], v[7])};
;       *(u32x4*)(dst + (size_t)(n0a + nl) * K + k0a + ks) = w; }
;     if (has1) { float v[8];
; #pragma unroll
;       for (int j = 0; j < 8; ++j) v[j] = tile[4160 + (ks + j) * 65 + nl];
;       u32x4 w = {cvt_pk_bf16(v[0], v[1]), cvt_pk_bf16(v[2], v[3]), cvt_pk_bf16(v[4], v[5]), cvt_pk_bf16(v[6], v[7])};
;       *(u32x4*)(dst + (size_t)(n0b + nl) * K + k0b + ks) = w; }
.Lcvo_p0:
	ds_write_b32 v2, v30 offset:0
	ds_write_b32 v2, v31 offset:2080
	ds_write_b32 v2, v32 offset:4160
	ds_write_b32 v2, v33 offset:6240
	ds_write_b32 v2, v34 offset:8320
	ds_write_b32 v2, v35 offset:10400
	ds_write_b32 v2, v36 offset:12480
	ds_write_b32 v2, v37 offset:14560
	s_cmp_lt_u32 s4, 0x400
	s_cselect_b32 s20, 4, 6
	s_cselect_b32 s21, 17, 19
	s_cselect_b32 s8, 11, 13
	s_mov_b32 s9, 0x9280000
	s_cselect_b32 s9, 0x8a80000, s9
	s_and_b32 s22, s4, 0x3ff
	s_lshl_b32 s25, 1, s20
	s_sub_u32 s25, s25, 1
	s_and_b32 s23, s22, s25
	s_lshr_b32 s24, s22, s20
	s_lshl_b32 s24, s24, s21
	s_lshl_b32 s23, s23, 7
	s_add_u32 s24, s24, s23
	s_add_u32 s24, s24, s9
	s_add_u32 s26, s14, s24
	s_addc_u32 s27, s15, 0
	v_lshlrev_b32_e32 v6, s8, v4
	v_add_u32_e32 v6, v6, v5
	s_waitcnt lgkmcnt(0)
	s_barrier
	ds_read_b32 v50, v3 offset:0
	ds_read_b32 v51, v3 offset:260
	ds_read_b32 v52, v3 offset:520
	ds_read_b32 v53, v3 offset:780
	ds_read_b32 v54, v3 offset:1040
	ds_read_b32 v55, v3 offset:1300
	ds_read_b32 v56, v3 offset:1560
	ds_read_b32 v57, v3 offset:1820
	s_waitcnt lgkmcnt(0)
	v_cvt_pk_bf16_f32 v60, v50, v51
	v_cvt_pk_bf16_f32 v61, v52, v53
	v_cvt_pk_bf16_f32 v62, v54, v55
	v_cvt_pk_bf16_f32 v63, v56, v57
	global_store_dwordx4 v6, v[60:63], s[26:27]
	s_add_u32 s7, s7, 1
	s_add_u32 s4, s4, 244
	s_cmp_lt_u32 s4, 0x800
	s_cbranch_scc0 .Lcvo_done
.Lcvo_j1:
	s_add_u32 s5, s4, 488
	s_cmp_lt_u32 s5, 0x800
	s_cbranch_scc0 .Lcvo_t1
	s_cmp_lt_u32 s5, 0x400
	s_cselect_b32 s20, 4, 6
	s_cselect_b32 s21, 14, 12
	s_cselect_b32 s26, s10, s12
	s_cselect_b32 s27, s11, s13
	s_and_b32 s22, s5, 0x3ff
	s_lshl_b32 s25, 1, s20
	s_sub_u32 s25, s25, 1
	s_and_b32 s23, s22, s25
	s_lshr_b32 s24, s22, s20
	s_lshl_b32 s23, s23, 6
	s_add_u32 s23, s23, s6
	s_lshl_b32 s23, s23, s21
	s_lshl_b32 s24, s24, 8
	s_add_u32 s23, s23, s24
	s_add_u32 s26, s26, s23
	s_addc_u32 s27, s27, 0
	s_add_u32 s25, s21, 3
	s_lshl_b32 s25, 1, s25
	v_add_u32_e32 v21, s25, v1
	v_add_u32_e32 v22, s25, v21
	v_add_u32_e32 v23, s25, v22
	v_add_u32_e32 v24, s25, v23
	v_add_u32_e32 v25, s25, v24
	v_add_u32_e32 v26, s25, v25
	v_add_u32_e32 v27, s25, v26
	global_load_dword v30, v1, s[26:27]
	global_load_dword v31, v21, s[26:27]
	global_load_dword v32, v22, s[26:27]
	global_load_dword v33, v23, s[26:27]
	global_load_dword v34, v24, s[26:27]
	global_load_dword v35, v25, s[26:27]
	global_load_dword v36, v26, s[26:27]
	global_load_dword v37, v27, s[26:27]
	s_cmp_lt_u32 s7, 2
	s_cbranch_scc1 .Lcvo_w1
	s_waitcnt vmcnt(18)
	s_branch .Lcvo_p1

; __device__ __forceinline__ unsigned cvt_pk_bf16(float lo, float hi) { unsigned r; asm volatile("v_cvt_pk_bf16_f32 %0, %1, %2" : "=v"(r) : "v"(lo), "v"(hi)); return r; }
; __device__ __forceinline__ void conv_matrix(const float* __restrict__ src, int K, int N, int Npad, bf16_t* __restrict__ dst, const float* __restrict__ scale, float* tile) {
;     ...
;   for (int i0 = blockIdx.x; i0 < tot; i0 += 2 * gridDim.x) {
;     const int i1 = i0 + gridDim.x; const bool has1 = i1 < tot;
;     const int k0a = (i0 % nk) * 64, n0a = (i0 / nk) * 64, k0b = has1 ? (i1 % nk) * 64 : 0, n0b = has1 ? (i1 / nk) * 64 : 0;
;     float va[8], vb[8];
; #pragma unroll
;     for (int i = 0; i < 8; ++i) { const int k = k0a + ty + 8 * i, n = n0a + tx; float v = (n < N) ? src[(size_t)k * N + n] : 0.f; if (scale) v *= scale[k]; va[i] = v; }
;     if (has1) {
; #pragma unroll
;       for (int i = 0; i < 8; ++i) { const int k = k0b + ty + 8 * i, n = n0b + tx; float v = (n < N) ? src[(size_t)k * N + n] : 0.f; if (scale) v *= scale[k]; vb[i] = v; }
;     }
;     __syncthreads();
; #pragma unroll
;     for (int i = 0; i < 8; ++i) { tile[(ty + 8 * i) * 65 + tx] = va[i]; if (has1) tile[4160 + (ty + 8 * i) * 65 + tx] = vb[i]; }
;     __syncthreads();
;     { float v[8];
; #pragma unroll
;       for (int j = 0; j < 8; ++j) v[j] = tile[(ks + j) * 65 + nl];
;       u32x4 w = {cvt_pk_bf16(v[0], v[1]), cvt_pk_bf16(v[2], v[3]), cvt_pk_bf16(v[4], v[5]), cvt_pk_bf16(v[6], v[7])};
;       *(u32x4*)(dst + (size_t)(n0a + nl) * K + k0a + ks) = w; }
;     if (has1) { float v[8];
; #pragma unroll
;       for (int j = 0; j < 8; ++j) v[j] = tile[4160 + (ks + j) * 65 + nl];
;       u32x4 w = {cvt_pk_bf16(v[0], v[1]), cvt_pk_bf16(v[2], v[3]), cvt_pk_bf16(v[4], v[5]), cvt_pk_bf16(v[6], v[7])};
;       *(u32x4*)(dst + (size_t)(n0b + nl) * K + k0b + ks) = w; }
.Lcvo_p1:
	ds_write_b32 v2, v40 offset:16640
	ds_write_b32 v2, v41 offset:18720
	ds_write_b32 v2, v42 offset:20800
	ds_write_b32 v2, v43 offset:22880
	ds_write_b32 v2, v44 offset:24960
	ds_write_b32 v2, v45 offset:27040
	ds_write_b32 v2, v46 offset:29120
	ds_write_b32 v2, v47 offset:31200
	s_cmp_lt_u32 s4, 0x400
	s_cselect_b32 s20, 4, 6
	s_cselect_b32 s21, 17, 19
	s_cselect_b32 s8, 11, 13
	s_mov_b32 s9, 0x9280000
	s_cselect_b32 s9, 0x8a80000, s9
	s_and_b32 s22, s4, 0x3ff
	s_lshl_b32 s25, 1, s20
	s_sub_u32 s25, s25, 1
	s_and_b32 s23, s22, s25
	s_lshr_b32 s24, s22, s20
	s_lshl_b32 s24, s24, s21
	s_lshl_b32 s23, s23, 7
	s_add_u32 s24, s24, s23
	s_add_u32 s24, s24, s9
	s_add_u32 s26, s14, s24
	s_addc_u32 s27, s15, 0
	v_lshlrev_b32_e32 v6, s8, v4
	v_add_u32_e32 v6, v6, v5
	s_waitcnt lgkmcnt(0)
	s_barrier
	ds_read_b32 v50, v3 offset:16640
	ds_read_b32 v51, v3 offset:16900
	ds_read_b32 v52, v3 offset:17160
	ds_read_b32 v53, v3 offset:17420
	ds_read_b32 v54, v3 offset:17680
	ds_read_b32 v55, v3 offset:17940
	ds_read_b32 v56, v3 offset:18200
	ds_read_b32 v57, v3 offset:18460
	s_waitcnt lgkmcnt(0)
	v_cvt_pk_bf16_f32 v60, v50, v51
	v_cvt_pk_bf16_f32 v61, v52, v53
	v_cvt_pk_bf16_f32 v62, v54, v55
	v_cvt_pk_bf16_f32 v63, v56, v57
	global_store_dwordx4 v6, v[60:63], s[26:27]
	s_add_u32 s7, s7, 1
	s_add_u32 s4, s4, 244
	s_cmp_lt_u32 s4, 0x800
	s_cbranch_scc0 .Lcvo_done
.Lcvo_j2:
	s_add_u32 s5, s4, 488
	s_cmp_lt_u32 s5, 0x800
	s_cbranch_scc0 .Lcvo_t2
	s_cmp_lt_u32 s5, 0x400
	s_cselect_b32 s20, 4, 6
	s_cselect_b32 s21, 14, 12
	s_cselect_b32 s26, s10, s12
	s_cselect_b32 s27, s11, s13
	s_and_b32 s22, s5, 0x3ff
	s_lshl_b32 s25, 1, s20
	s_sub_u32 s25, s25, 1
	s_and_b32 s23, s22, s25
	s_lshr_b32 s24, s22, s20
	s_lshl_b32 s23, s23, 6
	s_add_u32 s23, s23, s6
	s_lshl_b32 s23, s23, s21
	s_lshl_b32 s24, s24, 8
	s_add_u32 s23, s23, s24
	s_add_u32 s26, s26, s23
	s_addc_u32 s27, s27, 0
	s_add_u32 s25, s21, 3
	s_lshl_b32 s25, 1, s25
	v_add_u32_e32 v21, s25, v1
	v_add_u32_e32 v22, s25, v21
	v_add_u32_e32 v23, s25, v22
	v_add_u32_e32 v24, s25, v23
	v_add_u32_e32 v25, s25, v24
	v_add_u32_e32 v26, s25, v25
	v_add_u32_e32 v27, s25, v26
	global_load_dword v40, v1, s[26:27]
	global_load_dword v41, v21, s[26:27]
	global_load_dword v42, v22, s[26:27]
	global_load_dword v43, v23, s[26:27]
	global_load_dword v44, v24, s[26:27]
	global_load_dword v45, v25, s[26:27]
	global_load_dword v46, v26, s[26:27]
	global_load_dword v47, v27, s[26:27]
	s_cmp_lt_u32 s7, 2
	s_cbranch_scc1 .Lcvo_w2
	s_waitcnt vmcnt(18)
	s_branch .Lcvo_p2

; __device__ __forceinline__ unsigned cvt_pk_bf16(float lo, float hi) { unsigned r; asm volatile("v_cvt_pk_bf16_f32 %0, %1, %2" : "=v"(r) : "v"(lo), "v"(hi)); return r; }
; __device__ __forceinline__ void conv_matrix(const float* __restrict__ src, int K, int N, int Npad, bf16_t* __restrict__ dst, const float* __restrict__ scale, float* tile) {
;     ...
;     __syncthreads();
; #pragma unroll
;     for (int i = 0; i < 8; ++i) { tile[(ty + 8 * i) * 65 + tx] = va[i]; if (has1) tile[4160 + (ty + 8 * i) * 65 + tx] = vb[i]; }
;     __syncthreads();
;     { float v[8];
; #pragma unroll
;       for (int j = 0; j < 8; ++j) v[j] = tile[(ks + j) * 65 + nl];
;       u32x4 w = {cvt_pk_bf16(v[0], v[1]), cvt_pk_bf16(v[2], v[3]), cvt_pk_bf16(v[4], v[5]), cvt_pk_bf16(v[6], v[7])};
;       *(u32x4*)(dst + (size_t)(n0a + nl) * K + k0a + ks) = w; }
;     if (has1) { float v[8];
; #pragma unroll
;       for (int j = 0; j < 8; ++j) v[j] = tile[4160 + (ks + j) * 65 + nl];
;       u32x4 w = {cvt_pk_bf16(v[0], v[1]), cvt_pk_bf16(v[2], v[3]), cvt_pk_bf16(v[4], v[5]), cvt_pk_bf16(v[6], v[7])};
;       *(u32x4*)(dst + (size_t)(n0b + nl) * K + k0b + ks) = w; }
.Lcvo_p2:
	ds_write_b32 v2, v8 offset:33280
	ds_write_b32 v2, v9 offset:35360
	ds_write_b32 v2, v10 offset:37440
	ds_write_b32 v2, v11 offset:39520
	ds_write_b32 v2, v12 offset:41600
	ds_write_b32 v2, v13 offset:43680
	ds_write_b32 v2, v14 offset:45760
	ds_write_b32 v2, v15 offset:47840
	s_cmp_lt_u32 s4, 0x400
	s_cselect_b32 s20, 4, 6
	s_cselect_b32 s21, 17, 19
	s_cselect_b32 s8, 11, 13
	s_mov_b32 s9, 0x9280000
	s_cselect_b32 s9, 0x8a80000, s9
	s_and_b32 s22, s4, 0x3ff
	s_lshl_b32 s25, 1, s20
	s_sub_u32 s25, s25, 1
	s_and_b32 s23, s22, s25
	s_lshr_b32 s24, s22, s20
	s_lshl_b32 s24, s24, s21
	s_lshl_b32 s23, s23, 7
	s_add_u32 s24, s24, s23
	s_add_u32 s24, s24, s9
	s_add_u32 s26, s14, s24
	s_addc_u32 s27, s15, 0
	v_lshlrev_b32_e32 v6, s8, v4
	v_add_u32_e32 v6, v6, v5
	s_waitcnt lgkmcnt(0)
	s_barrier
	ds_read_b32 v50, v3 offset:33280
	ds_read_b32 v51, v3 offset:33540
	ds_read_b32 v52, v3 offset:33800
	ds_read_b32 v53, v3 offset:34060
	ds_read_b32 v54, v3 offset:34320
	ds_read_b32 v55, v3 offset:34580
	ds_read_b32 v56, v3 offset:34840
	ds_read_b32 v57, v3 offset:35100
	s_waitcnt lgkmcnt(0)
	v_cvt_pk_bf16_f32 v60, v50, v51
	v_cvt_pk_bf16_f32 v61, v52, v53
	v_cvt_pk_bf16_f32 v62, v54, v55
	v_cvt_pk_bf16_f32 v63, v56, v57
	global_store_dwordx4 v6, v[60:63], s[26:27]
	s_add_u32 s7, s7, 1
	s_add_u32 s4, s4, 244
	s_cmp_lt_u32 s4, 0x800
	s_cbranch_scc0 .Lcvo_done
	s_branch .Lcvo_j0

; __device__ __forceinline__ int tid_() { int t = threadIdx.x; asm volatile("" : "+v"(t)); return t; }
; __device__ __forceinline__ void conv_matrix(const float* __restrict__ src, int K, int N, int Npad, bf16_t* __restrict__ dst, const float* __restrict__ scale, float* tile) {
;   const int nk = K / 64, nn = Npad / 64, tot = nk * nn;
;   const int tid = tid_(), tx = tid & 63, ty = tid >> 6, nl = tid >> 3, ks = (tid & 7) * 8;
;   for (int i0 = blockIdx.x; i0 < tot; i0 += 2 * gridDim.x) {
;     const int i1 = i0 + gridDim.x; const bool has1 = i1 < tot;
;     const int k0a = (i0 % nk) * 64, n0a = (i0 / nk) * 64, k0b = has1 ? (i1 % nk) * 64 : 0, n0b = has1 ? (i1 / nk) * 64 : 0;
;     float va[8], vb[8];
; #pragma unroll
;     for (int i = 0; i < 8; ++i) { const int k = k0a + ty + 8 * i, n = n0a + tx; float v = (n < N) ? src[(size_t)k * N + n] : 0.f; if (scale) v *= scale[k]; va[i] = v; }
;     if (has1) {
; #pragma unroll
;       for (int i = 0; i < 8; ++i) { const int k = k0b + ty + 8 * i, n = n0b + tx; float v = (n < N) ? src[(size_t)k * N + n] : 0.f; if (scale) v *= scale[k]; vb[i] = v; }
;     }
.LBB0_2057:
	s_cmp_lt_u32 s2, 77
	s_cbranch_scc1 .Lcve_skip
	v_writelane_b32 v255, s4, 46
	v_writelane_b32 v255, s5, 47
	v_writelane_b32 v255, s10, 48
	v_writelane_b32 v255, s11, 49
	v_writelane_b32 v255, s12, 50
	v_writelane_b32 v255, s13, 51
	v_writelane_b32 v255, s14, 52
	v_writelane_b32 v255, s15, 53
	v_writelane_b32 v255, s20, 54
	v_writelane_b32 v255, s21, 55
	v_writelane_b32 v255, s22, 56
	v_writelane_b32 v255, s23, 57
	v_writelane_b32 v255, s24, 58
	v_writelane_b32 v255, s25, 59
	v_writelane_b32 v255, s26, 60
	v_writelane_b32 v255, s27, 61
	s_load_dwordx2 s[10:11], s[0:1], 0x40
	s_load_dwordx2 s[12:13], s[0:1], 0x48
	s_load_dwordx2 s[14:15], s[0:1], 0xd8
	v_and_b32_e32 v1, 63, v187
	v_lshrrev_b32_e32 v7, 6, v187
	v_lshrrev_b32_e32 v4, 3, v187
	v_and_b32_e32 v5, 7, v187
	s_nop 1
	v_readfirstlane_b32 s6, v7
	v_readlane_b32 s7, v255, 32
	v_mul_u32_u24_e32 v2, 0x41, v7
	v_add_u32_e32 v2, v2, v1
	v_lshlrev_b32_e32 v2, 2, v2
	v_add_u32_e32 v2, 16, v2
	v_lshlrev_b32_e32 v1, 2, v1
	v_mul_u32_u24_e32 v3, 0x208, v5
	v_add_u32_e32 v3, v3, v4
	v_lshlrev_b32_e32 v3, 2, v3
	v_add_u32_e32 v3, 16, v3
	v_lshlrev_b32_e32 v5, 4, v5
	s_lshl_b32 s7, s7, 24
	s_waitcnt lgkmcnt(0)
	s_add_u32 s10, s10, s7
	s_addc_u32 s11, s11, 0
	s_add_u32 s12, s12, s7
	s_addc_u32 s13, s13, 0
	s_sub_u32 s4, s2, 77
	s_cmp_lt_u32 s4, 0x400
	s_cselect_b32 s20, 4, 6
	s_cselect_b32 s21, 14, 12
	s_cselect_b32 s26, s10, s12
	s_cselect_b32 s27, s11, s13
	s_and_b32 s22, s4, 0x3ff
	s_lshl_b32 s25, 1, s20
	s_sub_u32 s25, s25, 1
	s_and_b32 s23, s22, s25
	s_lshr_b32 s24, s22, s20
	s_lshl_b32 s23, s23, 6
	s_add_u32 s23, s23, s6
	s_lshl_b32 s23, s23, s21
	s_lshl_b32 s24, s24, 8
	s_add_u32 s23, s23, s24
	s_add_u32 s26, s26, s23
	s_addc_u32 s27, s27, 0
	s_add_u32 s25, s21, 3
	s_lshl_b32 s25, 1, s25
	v_add_u32_e32 v21, s25, v1
	v_add_u32_e32 v22, s25, v21
	v_add_u32_e32 v23, s25, v22
	v_add_u32_e32 v24, s25, v23
	v_add_u32_e32 v25, s25, v24
	v_add_u32_e32 v26, s25, v25
	v_add_u32_e32 v27, s25, v26
	global_load_dword v30, v1, s[26:27]
	global_load_dword v31, v21, s[26:27]
	global_load_dword v32, v22, s[26:27]
	global_load_dword v33, v23, s[26:27]
	global_load_dword v34, v24, s[26:27]
	global_load_dword v35, v25, s[26:27]
	global_load_dword v36, v26, s[26:27]
	global_load_dword v37, v27, s[26:27]
	s_add_u32 s5, s4, 179
	s_cmp_lt_u32 s5, 0x400
	s_cselect_b32 s20, 4, 6
	s_cselect_b32 s21, 14, 12
	s_cselect_b32 s26, s10, s12
	s_cselect_b32 s27, s11, s13
	s_and_b32 s22, s5, 0x3ff
	s_lshl_b32 s25, 1, s20
	s_sub_u32 s25, s25, 1
	s_and_b32 s23, s22, s25
	s_lshr_b32 s24, s22, s20
	s_lshl_b32 s23, s23, 6
	s_add_u32 s23, s23, s6
	s_lshl_b32 s23, s23, s21
	s_lshl_b32 s24, s24, 8
	s_add_u32 s23, s23, s24
	s_add_u32 s26, s26, s23
	s_addc_u32 s27, s27, 0
	s_add_u32 s25, s21, 3
	s_lshl_b32 s25, 1, s25
	v_add_u32_e32 v21, s25, v1
	v_add_u32_e32 v22, s25, v21
	v_add_u32_e32 v23, s25, v22
	v_add_u32_e32 v24, s25, v23
	v_add_u32_e32 v25, s25, v24
	v_add_u32_e32 v26, s25, v25
	v_add_u32_e32 v27, s25, v26
	global_load_dword v40, v1, s[26:27]
	global_load_dword v41, v21, s[26:27]
	global_load_dword v42, v22, s[26:27]
	global_load_dword v43, v23, s[26:27]
	global_load_dword v44, v24, s[26:27]
	global_load_dword v45, v25, s[26:27]
	global_load_dword v46, v26, s[26:27]
	global_load_dword v47, v27, s[26:27]
	s_mov_b32 s7, 0
.Lcve_j0:
	s_add_u32 s5, s4, 358
	s_cmp_lt_u32 s5, 0x800
	s_cbranch_scc0 .Lcve_t0
	s_cmp_lt_u32 s5, 0x400
	s_cselect_b32 s20, 4, 6
	s_cselect_b32 s21, 14, 12
	s_cselect_b32 s26, s10, s12
	s_cselect_b32 s27, s11, s13
	s_and_b32 s22, s5, 0x3ff
	s_lshl_b32 s25, 1, s20
	s_sub_u32 s25, s25, 1
	s_and_b32 s23, s22, s25
	s_lshr_b32 s24, s22, s20
	s_lshl_b32 s23, s23, 6
	s_add_u32 s23, s23, s6
	s_lshl_b32 s23, s23, s21
	s_lshl_b32 s24, s24, 8
	s_add_u32 s23, s23, s24
	s_add_u32 s26, s26, s23
	s_addc_u32 s27, s27, 0
	s_add_u32 s25, s21, 3
	s_lshl_b32 s25, 1, s25
	v_add_u32_e32 v21, s25, v1
	v_add_u32_e32 v22, s25, v21
	v_add_u32_e32 v23, s25, v22
	v_add_u32_e32 v24, s25, v23
	v_add_u32_e32 v25, s25, v24
	v_add_u32_e32 v26, s25, v25
	v_add_u32_e32 v27, s25, v26
	global_load_dword v8, v1, s[26:27]
	global_load_dword v9, v21, s[26:27]
	global_load_dword v10, v22, s[26:27]
	global_load_dword v11, v23, s[26:27]
	global_load_dword v12, v24, s[26:27]
	global_load_dword v13, v25, s[26:27]
	global_load_dword v14, v26, s[26:27]
	global_load_dword v15, v27, s[26:27]
	s_cmp_lt_u32 s7, 2
	s_cbranch_scc1 .Lcve_w0
	s_waitcnt vmcnt(18)
	s_branch .Lcve_p0

; __device__ __forceinline__ void conv_matrix(const float* __restrict__ src, int K, int N, int Npad, bf16_t* __restrict__ dst, const float* __restrict__ scale, float* tile) {
;     ...
;   for (int i0 = blockIdx.x; i0 < tot; i0 += 2 * gridDim.x) {
;     const int i1 = i0 + gridDim.x; const bool has1 = i1 < tot;
;     const int k0a = (i0 % nk) * 64, n0a = (i0 / nk) * 64, k0b = has1 ? (i1 % nk) * 64 : 0, n0b = has1 ? (i1 / nk) * 64 : 0;
;     float va[8], vb[8];
; #pragma unroll
;     for (int i = 0; i < 8; ++i) { const int k = k0a + ty + 8 * i, n = n0a + tx; float v = (n < N) ? src[(size_t)k * N + n] : 0.f; if (scale) v *= scale[k]; va[i] = v; }
;     if (has1) {
; #pragma unroll
;       for (int i = 0; i < 8; ++i) { const int k = k0b + ty + 8 * i, n = n0b + tx; float v = (n < N) ? src[(size_t)k * N + n] : 0.f; if (scale) v *= scale[k]; vb[i] = v; }
;     }
.Lcve_t0:
	s_add_u32 s5, s4, 179
	s_cmp_lt_u32 s5, 0x800
	s_cbranch_scc0 .Lcve_z0
	s_waitcnt vmcnt(8)
	s_branch .Lcve_p0

; __device__ __forceinline__ unsigned cvt_pk_bf16(float lo, float hi) { unsigned r; asm volatile("v_cvt_pk_bf16_f32 %0, %1, %2" : "=v"(r) : "v"(lo), "v"(hi)); return r; }
; __device__ __forceinline__ void conv_matrix(const float* __restrict__ src, int K, int N, int Npad, bf16_t* __restrict__ dst, const float* __restrict__ scale, float* tile) {
;     ...
;   for (int i0 = blockIdx.x; i0 < tot; i0 += 2 * gridDim.x) {
;     const int i1 = i0 + gridDim.x; const bool has1 = i1 < tot;
;     const int k0a = (i0 % nk) * 64, n0a = (i0 / nk) * 64, k0b = has1 ? (i1 % nk) * 64 : 0, n0b = has1 ? (i1 / nk) * 64 : 0;
;     float va[8], vb[8];
; #pragma unroll
;     for (int i = 0; i < 8; ++i) { const int k = k0a + ty + 8 * i, n = n0a + tx; float v = (n < N) ? src[(size_t)k * N + n] : 0.f; if (scale) v *= scale[k]; va[i] = v; }
;     if (has1) {
; #pragma unroll
;       for (int i = 0; i < 8; ++i) { const int k = k0b + ty + 8 * i, n = n0b + tx; float v = (n < N) ? src[(size_t)k * N + n] : 0.f; if (scale) v *= scale[k]; vb[i] = v; }
;     }
;     __syncthreads();
; #pragma unroll
;     for (int i = 0; i < 8; ++i) { tile[(ty + 8 * i) * 65 + tx] = va[i]; if (has1) tile[4160 + (ty + 8 * i) * 65 + tx] = vb[i]; }
;     __syncthreads();
;     { float v[8];
; #pragma unroll
;       for (int j = 0; j < 8; ++j) v[j] = tile[(ks + j) * 65 + nl];
;       u32x4 w = {cvt_pk_bf16(v[0], v[1]), cvt_pk_bf16(v[2], v[3]), cvt_pk_bf16(v[4], v[5]), cvt_pk_bf16(v[6], v[7])};
;       *(u32x4*)(dst + (size_t)(n0a + nl) * K + k0a + ks) = w; }
;     if (has1) { float v[8];
; #pragma unroll
;       for (int j = 0; j < 8; ++j) v[j] = tile[4160 + (ks + j) * 65 + nl];
;       u32x4 w = {cvt_pk_bf16(v[0], v[1]), cvt_pk_bf16(v[2], v[3]), cvt_pk_bf16(v[4], v[5]), cvt_pk_bf16(v[6], v[7])};
;       *(u32x4*)(dst + (size_t)(n0b + nl) * K + k0b + ks) = w; }
.Lcve_p0:
	ds_write_b32 v2, v30 offset:0
	ds_write_b32 v2, v31 offset:2080
	ds_write_b32 v2, v32 offset:4160
	ds_write_b32 v2, v33 offset:6240
	ds_write_b32 v2, v34 offset:8320
	ds_write_b32 v2, v35 offset:10400
	ds_write_b32 v2, v36 offset:12480
	ds_write_b32 v2, v37 offset:14560
	s_cmp_lt_u32 s4, 0x400
	s_cselect_b32 s20, 4, 6
	s_cselect_b32 s21, 17, 19
	s_cselect_b32 s8, 11, 13
	s_mov_b32 s9, 0x9280000
	s_cselect_b32 s9, 0x8a80000, s9
	s_and_b32 s22, s4, 0x3ff
	s_lshl_b32 s25, 1, s20
	s_sub_u32 s25, s25, 1
	s_and_b32 s23, s22, s25
	s_lshr_b32 s24, s22, s20
	s_lshl_b32 s24, s24, s21
	s_lshl_b32 s23, s23, 7
	s_add_u32 s24, s24, s23
	s_add_u32 s24, s24, s9
	s_add_u32 s26, s14, s24
	s_addc_u32 s27, s15, 0
	v_lshlrev_b32_e32 v6, s8, v4
	v_add_u32_e32 v6, v6, v5
	s_waitcnt lgkmcnt(0)
	s_barrier
	ds_read_b32 v50, v3 offset:0
	ds_read_b32 v51, v3 offset:260
	ds_read_b32 v52, v3 offset:520
	ds_read_b32 v53, v3 offset:780
	ds_read_b32 v54, v3 offset:1040
	ds_read_b32 v55, v3 offset:1300
	ds_read_b32 v56, v3 offset:1560
	ds_read_b32 v57, v3 offset:1820
	s_waitcnt lgkmcnt(0)
	v_cvt_pk_bf16_f32 v60, v50, v51
	v_cvt_pk_bf16_f32 v61, v52, v53
	v_cvt_pk_bf16_f32 v62, v54, v55
	v_cvt_pk_bf16_f32 v63, v56, v57
	global_store_dwordx4 v6, v[60:63], s[26:27]
	s_add_u32 s7, s7, 1
	s_add_u32 s4, s4, 179
	s_cmp_lt_u32 s4, 0x800
	s_cbranch_scc0 .Lcve_done
.Lcve_j1:
	s_add_u32 s5, s4, 358
	s_cmp_lt_u32 s5, 0x800
	s_cbranch_scc0 .Lcve_t1
	s_cmp_lt_u32 s5, 0x400
	s_cselect_b32 s20, 4, 6
	s_cselect_b32 s21, 14, 12
	s_cselect_b32 s26, s10, s12
	s_cselect_b32 s27, s11, s13
	s_and_b32 s22, s5, 0x3ff
	s_lshl_b32 s25, 1, s20
	s_sub_u32 s25, s25, 1
	s_and_b32 s23, s22, s25
	s_lshr_b32 s24, s22, s20
	s_lshl_b32 s23, s23, 6
	s_add_u32 s23, s23, s6
	s_lshl_b32 s23, s23, s21
	s_lshl_b32 s24, s24, 8
	s_add_u32 s23, s23, s24
	s_add_u32 s26, s26, s23
	s_addc_u32 s27, s27, 0
	s_add_u32 s25, s21, 3
	s_lshl_b32 s25, 1, s25
	v_add_u32_e32 v21, s25, v1
	v_add_u32_e32 v22, s25, v21
	v_add_u32_e32 v23, s25, v22
	v_add_u32_e32 v24, s25, v23
	v_add_u32_e32 v25, s25, v24
	v_add_u32_e32 v26, s25, v25
	v_add_u32_e32 v27, s25, v26
	global_load_dword v30, v1, s[26:27]
	global_load_dword v31, v21, s[26:27]
	global_load_dword v32, v22, s[26:27]
	global_load_dword v33, v23, s[26:27]
	global_load_dword v34, v24, s[26:27]
	global_load_dword v35, v25, s[26:27]
	global_load_dword v36, v26, s[26:27]
	global_load_dword v37, v27, s[26:27]
	s_cmp_lt_u32 s7, 2
	s_cbranch_scc1 .Lcve_w1
	s_waitcnt vmcnt(18)
	s_branch .Lcve_p1

; __device__ __forceinline__ unsigned cvt_pk_bf16(float lo, float hi) { unsigned r; asm volatile("v_cvt_pk_bf16_f32 %0, %1, %2" : "=v"(r) : "v"(lo), "v"(hi)); return r; }
; __device__ __forceinline__ void conv_matrix(const float* __restrict__ src, int K, int N, int Npad, bf16_t* __restrict__ dst, const float* __restrict__ scale, float* tile) {
;     ...
;   for (int i0 = blockIdx.x; i0 < tot; i0 += 2 * gridDim.x) {
;     const int i1 = i0 + gridDim.x; const bool has1 = i1 < tot;
;     const int k0a = (i0 % nk) * 64, n0a = (i0 / nk) * 64, k0b = has1 ? (i1 % nk) * 64 : 0, n0b = has1 ? (i1 / nk) * 64 : 0;
;     float va[8], vb[8];
; #pragma unroll
;     for (int i = 0; i < 8; ++i) { const int k = k0a + ty + 8 * i, n = n0a + tx; float v = (n < N) ? src[(size_t)k * N + n] : 0.f; if (scale) v *= scale[k]; va[i] = v; }
;     if (has1) {
; #pragma unroll
;       for (int i = 0; i < 8; ++i) { const int k = k0b + ty + 8 * i, n = n0b + tx; float v = (n < N) ? src[(size_t)k * N + n] : 0.f; if (scale) v *= scale[k]; vb[i] = v; }
;     }
;     __syncthreads();
; #pragma unroll
;     for (int i = 0; i < 8; ++i) { tile[(ty + 8 * i) * 65 + tx] = va[i]; if (has1) tile[4160 + (ty + 8 * i) * 65 + tx] = vb[i]; }
;     __syncthreads();
;     { float v[8];
; #pragma unroll
;       for (int j = 0; j < 8; ++j) v[j] = tile[(ks + j) * 65 + nl];
;       u32x4 w = {cvt_pk_bf16(v[0], v[1]), cvt_pk_bf16(v[2], v[3]), cvt_pk_bf16(v[4], v[5]), cvt_pk_bf16(v[6], v[7])};
;       *(u32x4*)(dst + (size_t)(n0a + nl) * K + k0a + ks) = w; }
;     if (has1) { float v[8];
; #pragma unroll
;       for (int j = 0; j < 8; ++j) v[j] = tile[4160 + (ks + j) * 65 + nl];
;       u32x4 w = {cvt_pk_bf16(v[0], v[1]), cvt_pk_bf16(v[2], v[3]), cvt_pk_bf16(v[4], v[5]), cvt_pk_bf16(v[6], v[7])};
;       *(u32x4*)(dst + (size_t)(n0b + nl) * K + k0b + ks) = w; }
.Lcve_p1:
	ds_write_b32 v2, v40 offset:16640
	ds_write_b32 v2, v41 offset:18720
	ds_write_b32 v2, v42 offset:20800
	ds_write_b32 v2, v43 offset:22880
	ds_write_b32 v2, v44 offset:24960
	ds_write_b32 v2, v45 offset:27040
	ds_write_b32 v2, v46 offset:29120
	ds_write_b32 v2, v47 offset:31200
	s_cmp_lt_u32 s4, 0x400
	s_cselect_b32 s20, 4, 6
	s_cselect_b32 s21, 17, 19
	s_cselect_b32 s8, 11, 13
	s_mov_b32 s9, 0x9280000
	s_cselect_b32 s9, 0x8a80000, s9
	s_and_b32 s22, s4, 0x3ff
	s_lshl_b32 s25, 1, s20
	s_sub_u32 s25, s25, 1
	s_and_b32 s23, s22, s25
	s_lshr_b32 s24, s22, s20
	s_lshl_b32 s24, s24, s21
	s_lshl_b32 s23, s23, 7
	s_add_u32 s24, s24, s23
	s_add_u32 s24, s24, s9
	s_add_u32 s26, s14, s24
	s_addc_u32 s27, s15, 0
	v_lshlrev_b32_e32 v6, s8, v4
	v_add_u32_e32 v6, v6, v5
	s_waitcnt lgkmcnt(0)
	s_barrier
	ds_read_b32 v50, v3 offset:16640
	ds_read_b32 v51, v3 offset:16900
	ds_read_b32 v52, v3 offset:17160
	ds_read_b32 v53, v3 offset:17420
	ds_read_b32 v54, v3 offset:17680
	ds_read_b32 v55, v3 offset:17940
	ds_read_b32 v56, v3 offset:18200
	ds_read_b32 v57, v3 offset:18460
	s_waitcnt lgkmcnt(0)
	v_cvt_pk_bf16_f32 v60, v50, v51
	v_cvt_pk_bf16_f32 v61, v52, v53
	v_cvt_pk_bf16_f32 v62, v54, v55
	v_cvt_pk_bf16_f32 v63, v56, v57
	global_store_dwordx4 v6, v[60:63], s[26:27]
	s_add_u32 s7, s7, 1
	s_add_u32 s4, s4, 179
	s_cmp_lt_u32 s4, 0x800
	s_cbranch_scc0 .Lcve_done
.Lcve_j2:
	s_add_u32 s5, s4, 358
	s_cmp_lt_u32 s5, 0x800
	s_cbranch_scc0 .Lcve_t2
	s_cmp_lt_u32 s5, 0x400
	s_cselect_b32 s20, 4, 6
	s_cselect_b32 s21, 14, 12
	s_cselect_b32 s26, s10, s12
	s_cselect_b32 s27, s11, s13
	s_and_b32 s22, s5, 0x3ff
	s_lshl_b32 s25, 1, s20
	s_sub_u32 s25, s25, 1
	s_and_b32 s23, s22, s25
	s_lshr_b32 s24, s22, s20
	s_lshl_b32 s23, s23, 6
	s_add_u32 s23, s23, s6
	s_lshl_b32 s23, s23, s21
	s_lshl_b32 s24, s24, 8
	s_add_u32 s23, s23, s24
	s_add_u32 s26, s26, s23
	s_addc_u32 s27, s27, 0
	s_add_u32 s25, s21, 3
	s_lshl_b32 s25, 1, s25
	v_add_u32_e32 v21, s25, v1
	v_add_u32_e32 v22, s25, v21
	v_add_u32_e32 v23, s25, v22
	v_add_u32_e32 v24, s25, v23
	v_add_u32_e32 v25, s25, v24
	v_add_u32_e32 v26, s25, v25
	v_add_u32_e32 v27, s25, v26
	global_load_dword v40, v1, s[26:27]
	global_load_dword v41, v21, s[26:27]
	global_load_dword v42, v22, s[26:27]
	global_load_dword v43, v23, s[26:27]
	global_load_dword v44, v24, s[26:27]
	global_load_dword v45, v25, s[26:27]
	global_load_dword v46, v26, s[26:27]
	global_load_dword v47, v27, s[26:27]
	s_cmp_lt_u32 s7, 2
	s_cbranch_scc1 .Lcve_w2
	s_waitcnt vmcnt(18)
	s_branch .Lcve_p2

; __device__ __forceinline__ unsigned cvt_pk_bf16(float lo, float hi) { unsigned r; asm volatile("v_cvt_pk_bf16_f32 %0, %1, %2" : "=v"(r) : "v"(lo), "v"(hi)); return r; }
; __device__ __forceinline__ void conv_matrix(const float* __restrict__ src, int K, int N, int Npad, bf16_t* __restrict__ dst, const float* __restrict__ scale, float* tile) {
;     ...
;     __syncthreads();
; #pragma unroll
;     for (int i = 0; i < 8; ++i) { tile[(ty + 8 * i) * 65 + tx] = va[i]; if (has1) tile[4160 + (ty + 8 * i) * 65 + tx] = vb[i]; }
;     __syncthreads();
;     { float v[8];
; #pragma unroll
;       for (int j = 0; j < 8; ++j) v[j] = tile[(ks + j) * 65 + nl];
;       u32x4 w = {cvt_pk_bf16(v[0], v[1]), cvt_pk_bf16(v[2], v[3]), cvt_pk_bf16(v[4], v[5]), cvt_pk_bf16(v[6], v[7])};
;       *(u32x4*)(dst + (size_t)(n0a + nl) * K + k0a + ks) = w; }
;     if (has1) { float v[8];
; #pragma unroll
;       for (int j = 0; j < 8; ++j) v[j] = tile[4160 + (ks + j) * 65 + nl];
;       u32x4 w = {cvt_pk_bf16(v[0], v[1]), cvt_pk_bf16(v[2], v[3]), cvt_pk_bf16(v[4], v[5]), cvt_pk_bf16(v[6], v[7])};
;       *(u32x4*)(dst + (size_t)(n0b + nl) * K + k0b + ks) = w; }
.Lcve_p2:
	ds_write_b32 v2, v8 offset:33280
	ds_write_b32 v2, v9 offset:35360
	ds_write_b32 v2, v10 offset:37440
	ds_write_b32 v2, v11 offset:39520
	ds_write_b32 v2, v12 offset:41600
	ds_write_b32 v2, v13 offset:43680
	ds_write_b32 v2, v14 offset:45760
	ds_write_b32 v2, v15 offset:47840
	s_cmp_lt_u32 s4, 0x400
	s_cselect_b32 s20, 4, 6
	s_cselect_b32 s21, 17, 19
	s_cselect_b32 s8, 11, 13
	s_mov_b32 s9, 0x9280000
	s_cselect_b32 s9, 0x8a80000, s9
	s_and_b32 s22, s4, 0x3ff
	s_lshl_b32 s25, 1, s20
	s_sub_u32 s25, s25, 1
	s_and_b32 s23, s22, s25
	s_lshr_b32 s24, s22, s20
	s_lshl_b32 s24, s24, s21
	s_lshl_b32 s23, s23, 7
	s_add_u32 s24, s24, s23
	s_add_u32 s24, s24, s9
	s_add_u32 s26, s14, s24
	s_addc_u32 s27, s15, 0
	v_lshlrev_b32_e32 v6, s8, v4
	v_add_u32_e32 v6, v6, v5
	s_waitcnt lgkmcnt(0)
	s_barrier
	ds_read_b32 v50, v3 offset:33280
	ds_read_b32 v51, v3 offset:33540
	ds_read_b32 v52, v3 offset:33800
	ds_read_b32 v53, v3 offset:34060
	ds_read_b32 v54, v3 offset:34320
	ds_read_b32 v55, v3 offset:34580
	ds_read_b32 v56, v3 offset:34840
	ds_read_b32 v57, v3 offset:35100
	s_waitcnt lgkmcnt(0)
	v_cvt_pk_bf16_f32 v60, v50, v51
	v_cvt_pk_bf16_f32 v61, v52, v53
	v_cvt_pk_bf16_f32 v62, v54, v55
	v_cvt_pk_bf16_f32 v63, v56, v57
	global_store_dwordx4 v6, v[60:63], s[26:27]
	s_add_u32 s7, s7, 1
	s_add_u32 s4, s4, 179
	s_cmp_lt_u32 s4, 0x800
	s_cbranch_scc0 .Lcve_done
	s_branch .Lcve_j0
